# out-proj epilogue (P3): bf16 residual stores staged through a per-wave LDS image so each wave-store writes 8 full 128-B lines instead of 16 half lines
# speedup vs baseline: 1.0105x; 1.0064x over previous
; #define LAS __attribute__((address_space(3)))
; __device__ __forceinline__ float fq_sum(float v) { v += __shfl_xor(v, 16); v += __shfl_xor(v, 32); return v; }
; __device__ __forceinline__ u32x4 pack8(f32x4 a, f32x4 b) { u32x4 w; w.x = pk2(a[0], a[1]); w.y = pk2(a[2], a[3]); w.z = pk2(b[0], b[1]); w.w = pk2(b[2], b[3]); return w; }
;     template <int KIND>
;     __device__ __forceinline__ void body(const f32x4 (&acc)[2][2][4][2], const pg8::Unit& u, int ui, int wr, int wc, int fr, int fq) const {
;     ...
;                     if (sw) *(LAS u32x4*)(sw + fr * 144 + bj * 64 + fq * 16) = pack8(v0, v1);
;                     else *(u32x4*)(rowp + bj * 32) = pack8(v0, v1);
;                     if (KIND == 4) { if (dst) { *(f32x4*)(dst + bj * 32) = v0; *(f32x4*)(dst + bj * 32 + 4) = v1; } }
;                 }
;                 if (sw) {
;                     bf16_t* gb = P + (size_t)(u.pm * 256 + ai * 128 + wr * 64 + m * 16 + srow) * DPROJ + u.pn * 256 + wc * 64 + spc * 8;
;                     const u32x4 w0 = *(const LAS u32x4*)(sw + srow * 144 + spc * 16), w1 = *(const LAS u32x4*)(sw + (srow + 8) * 144 + spc * 16);
;                     *(u32x4*)gb = w0; *(u32x4*)(gb + (size_t)8 * DPROJ) = w1;
;     __device__ __forceinline__ void operator()(const f32x4 (&acc)[2][2][4][2], const pg8::Unit& u, int ui, int wr, int wc, int fr, int fq) const {
;     ...
;                 const int row = row0 + ai * 128 + m * 16;
;                 const float rb = rl[ai * 128 + m * 16];
;                 float* o = out + (size_t)row * DM + col0; bf16_t* xo = xb + (size_t)row * DM + col0;
;                 float ss = 0.f;
; #pragma unroll
;                 for (int bj = 0; bj < 2; ++bj) {
;                     const f32x4 v0 = acc[ai][bj][m][0] * rb, v1 = acc[ai][bj][m][1] * rb;
;                     if (last) { *(f32x4*)(o + bj * 32) = v0; *(f32x4*)(o + bj * 32 + 4) = v1; }
;                     else *(u32x4*)(xo + bj * 32) = pack8(v0, v1);
;                     ss += (v0[0] * v0[0] + v0[1] * v0[1]) + (v0[2] * v0[2] + v0[3] * v0[3]) + (v1[0] * v1[0] + v1[1] * v1[1]) + (v1[2] * v1[2] + v1[3] * v1[3]);
;                 }
;                 ss = fq_sum(ss);
;                 if (fq == 0) ssx[(size_t)row * 32 + u.pn * 4 + wc] = ss;
.LBB0_647:
	s_lshl_b32 s9, s81, 2
	s_add_i32 s1, s1, s9
	v_lshrrev_b32_e32 v168, 6, v193
	v_lshrrev_b32_e32 v169, 4, v154
	v_and_b32_e32 v169, 12, v169
	v_add_u32_e32 v168, v168, v169
	v_mul_u32_u24_e32 v168, 0x900, v168
	v_add_u32_e32 v168, 0x23000, v168
	v_lshrrev_b32_e32 v169, 4, v185
	v_lshrrev_b32_e32 v170, 3, v185
	v_and_b32_e32 v171, 7, v185
	v_lshlrev_b32_e32 v161, 7, v192
	v_lshl_add_u32 v161, v192, 4, v161
	v_lshl_add_u32 v161, v169, 4, v161
	v_add_u32_e32 v161, v161, v168
	v_lshlrev_b32_e32 v160, 7, v170
	v_lshl_add_u32 v160, v170, 4, v160
	v_lshl_add_u32 v160, v171, 4, v160
	v_add_u32_e32 v160, v160, v168
	v_sub_u32_e32 v172, v170, v192
	v_lshlrev_b32_e32 v172, 12, v172
	v_sub_u32_e32 v173, v171, v169
	v_lshl_add_u32 v162, v173, 4, v172
	v_ashrrev_i32_e32 v163, 31, v162
	v_add_u32_e32 v164, 0x8000, v162
	v_ashrrev_i32_e32 v165, 31, v164
	v_lshl_add_u32 v146, v192, 2, s1
	ds_read_b32 v148, v146 offset:2048
	v_xor_b32_e32 v143, 16, v185
	v_cmp_lt_i32_e32 vcc, v143, v186
	v_lshl_add_u32 v142, s38, 8, v154
	v_lshl_add_u32 v140, s35, 8, v193
	s_waitcnt lgkmcnt(0)
	v_pk_mul_f32 v[20:21], v[20:21], v[148:149] op_sel_hi:[1,0]
	v_pk_mul_f32 v[158:159], v[18:19], v[148:149] op_sel_hi:[1,0]
	v_cvt_pk_bf16_f32 v19, v20, v21
	v_mul_f32_e32 v147, v159, v159
	v_mul_f32_e32 v21, v21, v21
	v_pk_mul_f32 v[38:39], v[38:39], v[148:149] op_sel_hi:[1,0]
	v_fmac_f32_e32 v147, v158, v158
	v_fmac_f32_e32 v21, v20, v20
	v_add_f32_e32 v20, v147, v21
	v_mul_f32_e32 v21, v39, v39
	v_pk_mul_f32 v[40:41], v[40:41], v[148:149] op_sel_hi:[1,0]
	v_fmac_f32_e32 v21, v38, v38
	v_add_f32_e32 v20, v21, v20
	v_mul_f32_e32 v21, v41, v41
	v_fmac_f32_e32 v21, v40, v40
	v_pk_mul_f32 v[36:37], v[36:37], v[148:149] op_sel_hi:[1,0]
	v_pk_mul_f32 v[34:35], v[34:35], v[148:149] op_sel_hi:[1,0]
	v_add_f32_e32 v20, v21, v20
	v_mul_f32_e32 v21, v35, v35
	v_mul_f32_e32 v147, v37, v37
	v_pk_mul_f32 v[54:55], v[54:55], v[148:149] op_sel_hi:[1,0]
	v_fmac_f32_e32 v21, v34, v34
	v_fmac_f32_e32 v147, v36, v36
	v_add_f32_e32 v21, v21, v147
	v_mul_f32_e32 v147, v55, v55
	v_pk_mul_f32 v[56:57], v[56:57], v[148:149] op_sel_hi:[1,0]
	v_fmac_f32_e32 v147, v54, v54
	v_add_f32_e32 v21, v147, v21
	v_mul_f32_e32 v147, v57, v57
	v_cndmask_b32_e32 v143, v185, v143, vcc
	v_fmac_f32_e32 v147, v56, v56
	v_lshlrev_b32_e32 v145, 2, v143
	v_xor_b32_e32 v143, 32, v185
	v_add_f32_e32 v21, v147, v21
	v_cmp_lt_i32_e32 vcc, v143, v186
	v_add_f32_e32 v147, v20, v21
	ds_bpermute_b32 v148, v145, v147
	v_cndmask_b32_e32 v143, v185, v143, vcc
	v_lshlrev_b32_e32 v144, 2, v143
	v_ashrrev_i32_e32 v143, 31, v142
	v_lshlrev_b64 v[152:153], 12, v[142:143]
	v_ashrrev_i32_e32 v141, 31, v140
	v_lshl_add_u64 v[152:153], s[54:55], 0, v[152:153]
	v_lshl_add_u64 v[152:153], v[140:141], 1, v[152:153]
	v_cvt_pk_bf16_f32 v18, v158, v159
	v_cvt_pk_bf16_f32 v20, v38, v39
	v_cvt_pk_bf16_f32 v21, v40, v41
	ds_write_b128 v161, v[18:21]
	s_lshl_b32 s14, s35, 2
	s_ashr_i32 s15, s14, 31
	s_waitcnt lgkmcnt(0)
	v_add_f32_e32 v18, v147, v148
	ds_bpermute_b32 v19, v144, v18
	v_cvt_pk_bf16_f32 v34, v34, v35
	v_cvt_pk_bf16_f32 v35, v36, v37
	v_cvt_pk_bf16_f32 v36, v54, v55
	v_cvt_pk_bf16_f32 v37, v56, v57
	ds_write_b128 v161, v[34:37] offset:64
	ds_read_b128 v[168:171], v160
	ds_read_b128 v[172:175], v160 offset:1152
	v_lshl_add_u64 v[166:167], v[152:153], 0, v[162:163]
	s_waitcnt lgkmcnt(0)
	global_store_dwordx4 v[166:167], v[168:171], off
	v_lshl_add_u64 v[166:167], v[152:153], 0, v[164:165]
	s_nop 0
	global_store_dwordx4 v[166:167], v[172:175], off
	s_and_saveexec_b64 s[16:17], s[40:41]
	v_readlane_b32 s51, v255, 9
	s_cbranch_execz .LBB0_649
	s_waitcnt lgkmcnt(0)
	v_add_f32_e32 v20, v18, v19
	v_lshlrev_b64 v[18:19], 7, v[142:143]
	v_lshl_add_u64 v[18:19], s[56:57], 0, v[18:19]
	v_lshl_add_u64 v[18:19], s[14:15], 2, v[18:19]
	s_lshl_b32 s44, s95, 2
	v_lshl_add_u64 v[18:19], v[18:19], 0, s[44:45]
	global_store_dword v[18:19], v20, off
.LBB0_649:
	s_or_b64 exec, exec, s[16:17]
	ds_read_b32 v20, v146 offset:2112
	v_or_b32_e32 v18, 16, v142
	s_waitcnt lgkmcnt(0)
	v_ashrrev_i32_e32 v19, 31, v18
	v_lshlrev_b64 v[34:35], 12, v[18:19]
	v_lshl_add_u64 v[34:35], s[54:55], 0, v[34:35]
	v_pk_mul_f32 v[8:9], v[8:9], v[20:21] op_sel_hi:[1,0]
	v_pk_mul_f32 v[36:37], v[6:7], v[20:21] op_sel_hi:[1,0]
	v_pk_mul_f32 v[28:29], v[28:29], v[20:21] op_sel_hi:[1,0]
	v_pk_mul_f32 v[26:27], v[26:27], v[20:21] op_sel_hi:[1,0]
	v_cvt_pk_bf16_f32 v7, v8, v9
	v_mul_f32_e32 v21, v37, v37
	v_mul_f32_e32 v9, v9, v9
	v_fmac_f32_e32 v21, v36, v36
	v_fmac_f32_e32 v9, v8, v8
	v_add_f32_e32 v8, v21, v9
	v_mul_f32_e32 v9, v27, v27
	v_fmac_f32_e32 v9, v26, v26
	v_add_f32_e32 v8, v9, v8
	v_mul_f32_e32 v9, v29, v29
	v_fmac_f32_e32 v9, v28, v28
	v_pk_mul_f32 v[24:25], v[24:25], v[20:21] op_sel_hi:[1,0]
	v_pk_mul_f32 v[22:23], v[22:23], v[20:21] op_sel_hi:[1,0]
	v_cvt_pk_bf16_f32 v6, v36, v37
	v_add_f32_e32 v8, v9, v8
	v_pk_mul_f32 v[36:37], v[44:45], v[20:21] op_sel_hi:[1,0]
	v_pk_mul_f32 v[38:39], v[42:43], v[20:21] op_sel_hi:[1,0]
	v_mul_f32_e32 v9, v23, v23
	v_mul_f32_e32 v20, v25, v25
	v_fmac_f32_e32 v9, v22, v22
	v_fmac_f32_e32 v20, v24, v24
	v_add_f32_e32 v9, v9, v20
	v_mul_f32_e32 v20, v39, v39
	v_fmac_f32_e32 v20, v38, v38
	v_add_f32_e32 v9, v20, v9
	v_mul_f32_e32 v20, v37, v37
	v_fmac_f32_e32 v20, v36, v36
	v_add_f32_e32 v9, v20, v9
	v_add_f32_e32 v21, v8, v9
	ds_bpermute_b32 v40, v145, v21
	v_lshl_add_u64 v[34:35], v[140:141], 1, v[34:35]
	v_cvt_pk_bf16_f32 v8, v26, v27
	v_cvt_pk_bf16_f32 v9, v28, v29
	ds_write_b128 v161, v[6:9]
	v_cvt_pk_bf16_f32 v20, v22, v23
	v_cvt_pk_bf16_f32 v22, v38, v39
	s_waitcnt lgkmcnt(0)
	v_add_f32_e32 v6, v21, v40
	ds_bpermute_b32 v7, v144, v6
	v_cvt_pk_bf16_f32 v21, v24, v25
	v_cvt_pk_bf16_f32 v23, v36, v37
	ds_write_b128 v161, v[20:23] offset:64
	ds_read_b128 v[176:179], v160
	ds_read_b128 v[180:183], v160 offset:1152
	v_lshl_add_u64 v[166:167], v[34:35], 0, v[162:163]
	s_waitcnt lgkmcnt(0)
	global_store_dwordx4 v[166:167], v[176:179], off
	v_lshl_add_u64 v[166:167], v[34:35], 0, v[164:165]
	s_nop 0
	global_store_dwordx4 v[166:167], v[180:183], off
	s_and_saveexec_b64 s[16:17], s[40:41]
	s_cbranch_execz .LBB0_651
	s_waitcnt lgkmcnt(0)
	v_add_f32_e32 v8, v6, v7
	v_lshlrev_b64 v[6:7], 7, v[18:19]
	v_lshl_add_u64 v[6:7], s[56:57], 0, v[6:7]
	v_lshl_add_u64 v[6:7], s[14:15], 2, v[6:7]
	s_lshl_b32 s44, s95, 2
	v_lshl_add_u64 v[6:7], v[6:7], 0, s[44:45]
	global_store_dword v[6:7], v8, off
; #define LAS __attribute__((address_space(3)))
; __device__ __forceinline__ float fq_sum(float v) { v += __shfl_xor(v, 16); v += __shfl_xor(v, 32); return v; }
; __device__ __forceinline__ u32x4 pack8(f32x4 a, f32x4 b) { u32x4 w; w.x = pk2(a[0], a[1]); w.y = pk2(a[2], a[3]); w.z = pk2(b[0], b[1]); w.w = pk2(b[2], b[3]); return w; }
;     template <int KIND>
;     __device__ __forceinline__ void body(const f32x4 (&acc)[2][2][4][2], const pg8::Unit& u, int ui, int wr, int wc, int fr, int fq) const {
;     ...
;                 if (sw) {
;                     bf16_t* gb = P + (size_t)(u.pm * 256 + ai * 128 + wr * 64 + m * 16 + srow) * DPROJ + u.pn * 256 + wc * 64 + spc * 8;
;                     const u32x4 w0 = *(const LAS u32x4*)(sw + srow * 144 + spc * 16), w1 = *(const LAS u32x4*)(sw + (srow + 8) * 144 + spc * 16);
;                     *(u32x4*)gb = w0; *(u32x4*)(gb + (size_t)8 * DPROJ) = w1;
;     __device__ __forceinline__ void operator()(const f32x4 (&acc)[2][2][4][2], const pg8::Unit& u, int ui, int wr, int wc, int fr, int fq) const {
;     ...
;                 const int row = row0 + ai * 128 + m * 16;
;                 const float rb = rl[ai * 128 + m * 16];
;                 float* o = out + (size_t)row * DM + col0; bf16_t* xo = xb + (size_t)row * DM + col0;
;                 float ss = 0.f;
; #pragma unroll
;                 for (int bj = 0; bj < 2; ++bj) {
;                     const f32x4 v0 = acc[ai][bj][m][0] * rb, v1 = acc[ai][bj][m][1] * rb;
;                     if (last) { *(f32x4*)(o + bj * 32) = v0; *(f32x4*)(o + bj * 32 + 4) = v1; }
;                     else *(u32x4*)(xo + bj * 32) = pack8(v0, v1);
;                     ss += (v0[0] * v0[0] + v0[1] * v0[1]) + (v0[2] * v0[2] + v0[3] * v0[3]) + (v1[0] * v1[0] + v1[1] * v1[1]) + (v1[2] * v1[2] + v1[3] * v1[3]);
;                 }
;                 ss = fq_sum(ss);
;                 if (fq == 0) ssx[(size_t)row * 32 + u.pn * 4 + wc] = ss;
.LBB0_651:
	s_or_b64 exec, exec, s[16:17]
	ds_read_b32 v8, v146 offset:2176
	v_or_b32_e32 v6, 32, v142
	s_waitcnt lgkmcnt(0)
	v_ashrrev_i32_e32 v7, 31, v6
	v_lshlrev_b64 v[18:19], 12, v[6:7]
	v_lshl_add_u64 v[18:19], s[54:55], 0, v[18:19]
	v_pk_mul_f32 v[4:5], v[4:5], v[8:9] op_sel_hi:[1,0]
	v_pk_mul_f32 v[20:21], v[2:3], v[8:9] op_sel_hi:[1,0]
	v_pk_mul_f32 v[16:17], v[16:17], v[8:9] op_sel_hi:[1,0]
	v_pk_mul_f32 v[14:15], v[14:15], v[8:9] op_sel_hi:[1,0]
	v_cvt_pk_bf16_f32 v3, v4, v5
	v_mul_f32_e32 v9, v21, v21
	v_mul_f32_e32 v5, v5, v5
	v_fmac_f32_e32 v9, v20, v20
	v_fmac_f32_e32 v5, v4, v4
	v_add_f32_e32 v4, v9, v5
	v_mul_f32_e32 v5, v15, v15
	v_fmac_f32_e32 v5, v14, v14
	v_add_f32_e32 v4, v5, v4
	v_mul_f32_e32 v5, v17, v17
	v_fmac_f32_e32 v5, v16, v16
	v_pk_mul_f32 v[12:13], v[12:13], v[8:9] op_sel_hi:[1,0]
	v_pk_mul_f32 v[10:11], v[10:11], v[8:9] op_sel_hi:[1,0]
	v_cvt_pk_bf16_f32 v2, v20, v21
	v_add_f32_e32 v4, v5, v4
	v_pk_mul_f32 v[20:21], v[32:33], v[8:9] op_sel_hi:[1,0]
	v_pk_mul_f32 v[22:23], v[30:31], v[8:9] op_sel_hi:[1,0]
	v_mul_f32_e32 v5, v11, v11
	v_mul_f32_e32 v8, v13, v13
	v_fmac_f32_e32 v5, v10, v10
	v_fmac_f32_e32 v8, v12, v12
	v_add_f32_e32 v5, v5, v8
	v_mul_f32_e32 v8, v23, v23
	v_fmac_f32_e32 v8, v22, v22
	v_add_f32_e32 v5, v8, v5
	v_mul_f32_e32 v8, v21, v21
	v_fmac_f32_e32 v8, v20, v20
	v_add_f32_e32 v5, v8, v5
	v_add_f32_e32 v9, v4, v5
	ds_bpermute_b32 v24, v145, v9
	v_lshl_add_u64 v[18:19], v[140:141], 1, v[18:19]
	v_cvt_pk_bf16_f32 v4, v14, v15
	v_cvt_pk_bf16_f32 v5, v16, v17
	ds_write_b128 v161, v[2:5]
	v_cvt_pk_bf16_f32 v8, v10, v11
	v_cvt_pk_bf16_f32 v10, v22, v23
	s_waitcnt lgkmcnt(0)
	v_add_f32_e32 v2, v9, v24
	ds_bpermute_b32 v3, v144, v2
	v_cvt_pk_bf16_f32 v9, v12, v13
	v_cvt_pk_bf16_f32 v11, v20, v21
	ds_write_b128 v161, v[8:11] offset:64
	ds_read_b128 v[168:171], v160
	ds_read_b128 v[172:175], v160 offset:1152
	v_lshl_add_u64 v[166:167], v[18:19], 0, v[162:163]
	s_waitcnt lgkmcnt(0)
	global_store_dwordx4 v[166:167], v[168:171], off
	v_lshl_add_u64 v[166:167], v[18:19], 0, v[164:165]
	s_nop 0
	global_store_dwordx4 v[166:167], v[172:175], off
	s_and_saveexec_b64 s[16:17], s[40:41]
	s_cbranch_execz .LBB0_653
	s_waitcnt lgkmcnt(0)
	v_add_f32_e32 v4, v2, v3
	v_lshlrev_b64 v[2:3], 7, v[6:7]
	v_lshl_add_u64 v[2:3], s[56:57], 0, v[2:3]
	v_lshl_add_u64 v[2:3], s[14:15], 2, v[2:3]
	s_lshl_b32 s44, s95, 2
	v_lshl_add_u64 v[2:3], v[2:3], 0, s[44:45]
	global_store_dword v[2:3], v4, off
.LBB0_653:
	s_or_b64 exec, exec, s[16:17]
	ds_read_b32 v6, v146 offset:2240
	v_or_b32_e32 v2, 48, v142
	s_waitcnt lgkmcnt(0)
	v_ashrrev_i32_e32 v3, 31, v2
	v_lshlrev_b64 v[4:5], 12, v[2:3]
	v_lshl_add_u64 v[4:5], s[54:55], 0, v[4:5]
	v_pk_mul_f32 v[8:9], v[120:121], v[6:7] op_sel_hi:[1,0]
	v_pk_mul_f32 v[12:13], v[118:119], v[6:7] op_sel_hi:[1,0]
	v_lshl_add_u64 v[10:11], v[140:141], 1, v[4:5]
	v_pk_mul_f32 v[14:15], v[128:129], v[6:7] op_sel_hi:[1,0]
	v_pk_mul_f32 v[16:17], v[126:127], v[6:7] op_sel_hi:[1,0]
	v_cvt_pk_bf16_f32 v5, v8, v9
	v_mul_f32_e32 v7, v13, v13
	v_mul_f32_e32 v9, v9, v9
	v_fmac_f32_e32 v7, v12, v12
	v_fmac_f32_e32 v9, v8, v8
	v_mul_f32_e32 v8, v17, v17
	v_add_f32_e32 v7, v7, v9
	v_fmac_f32_e32 v8, v16, v16
	v_add_f32_e32 v7, v8, v7
	v_mul_f32_e32 v8, v15, v15
	v_fmac_f32_e32 v8, v14, v14
	v_add_f32_e32 v7, v8, v7
	v_cvt_pk_bf16_f32 v4, v12, v13
	v_pk_mul_f32 v[8:9], v[116:117], v[6:7] op_sel_hi:[1,0]
	v_pk_mul_f32 v[12:13], v[114:115], v[6:7] op_sel_hi:[1,0]
	v_pk_mul_f32 v[18:19], v[124:125], v[6:7] op_sel_hi:[1,0]
	v_pk_mul_f32 v[20:21], v[122:123], v[6:7] op_sel_hi:[1,0]
	v_mul_f32_e32 v6, v13, v13
	v_mul_f32_e32 v22, v9, v9
	v_fmac_f32_e32 v6, v12, v12
	v_fmac_f32_e32 v22, v8, v8
	v_add_f32_e32 v6, v6, v22
	v_mul_f32_e32 v22, v21, v21
	v_fmac_f32_e32 v22, v20, v20
	v_add_f32_e32 v6, v22, v6
	v_mul_f32_e32 v22, v19, v19
	v_fmac_f32_e32 v22, v18, v18
	v_add_f32_e32 v6, v22, v6
	v_add_f32_e32 v22, v7, v6
	ds_bpermute_b32 v23, v145, v22
	v_cvt_pk_bf16_f32 v6, v16, v17
	v_cvt_pk_bf16_f32 v7, v14, v15
	ds_write_b128 v161, v[4:7]
	s_waitcnt lgkmcnt(0)
	s_nop 0
	v_add_f32_e32 v4, v22, v23
	ds_bpermute_b32 v5, v144, v4
	v_cvt_pk_bf16_f32 v6, v12, v13
	v_cvt_pk_bf16_f32 v7, v8, v9
	v_cvt_pk_bf16_f32 v8, v20, v21
	v_cvt_pk_bf16_f32 v9, v18, v19
	ds_write_b128 v161, v[6:9] offset:64
	ds_read_b128 v[176:179], v160
	ds_read_b128 v[180:183], v160 offset:1152
	v_lshl_add_u64 v[166:167], v[10:11], 0, v[162:163]
	s_waitcnt lgkmcnt(0)
	global_store_dwordx4 v[166:167], v[176:179], off
	v_lshl_add_u64 v[166:167], v[10:11], 0, v[164:165]
	s_nop 0
	global_store_dwordx4 v[166:167], v[180:183], off
	s_and_saveexec_b64 s[16:17], s[40:41]
	s_cbranch_execz .LBB0_655
	v_lshlrev_b64 v[2:3], 7, v[2:3]
	v_lshl_add_u64 v[2:3], s[56:57], 0, v[2:3]
	v_lshl_add_u64 v[2:3], s[14:15], 2, v[2:3]
	s_lshl_b32 s44, s95, 2
	s_waitcnt lgkmcnt(0)
	v_add_f32_e32 v4, v4, v5
	v_lshl_add_u64 v[2:3], v[2:3], 0, s[44:45]
	global_store_dword v[2:3], v4, off
; #define LAS __attribute__((address_space(3)))
; __device__ __forceinline__ float fq_sum(float v) { v += __shfl_xor(v, 16); v += __shfl_xor(v, 32); return v; }
; __device__ __forceinline__ u32x4 pack8(f32x4 a, f32x4 b) { u32x4 w; w.x = pk2(a[0], a[1]); w.y = pk2(a[2], a[3]); w.z = pk2(b[0], b[1]); w.w = pk2(b[2], b[3]); return w; }
;     template <int KIND>
;     __device__ __forceinline__ void body(const f32x4 (&acc)[2][2][4][2], const pg8::Unit& u, int ui, int wr, int wc, int fr, int fq) const {
;     ...
;                 if (sw) {
;                     bf16_t* gb = P + (size_t)(u.pm * 256 + ai * 128 + wr * 64 + m * 16 + srow) * DPROJ + u.pn * 256 + wc * 64 + spc * 8;
;                     const u32x4 w0 = *(const LAS u32x4*)(sw + srow * 144 + spc * 16), w1 = *(const LAS u32x4*)(sw + (srow + 8) * 144 + spc * 16);
;                     *(u32x4*)gb = w0; *(u32x4*)(gb + (size_t)8 * DPROJ) = w1;
;     __device__ __forceinline__ void operator()(const f32x4 (&acc)[2][2][4][2], const pg8::Unit& u, int ui, int wr, int wc, int fr, int fq) const {
;     ...
;                 const int row = row0 + ai * 128 + m * 16;
;                 const float rb = rl[ai * 128 + m * 16];
;                 float* o = out + (size_t)row * DM + col0; bf16_t* xo = xb + (size_t)row * DM + col0;
;                 float ss = 0.f;
; #pragma unroll
;                 for (int bj = 0; bj < 2; ++bj) {
;                     const f32x4 v0 = acc[ai][bj][m][0] * rb, v1 = acc[ai][bj][m][1] * rb;
;                     if (last) { *(f32x4*)(o + bj * 32) = v0; *(f32x4*)(o + bj * 32 + 4) = v1; }
;                     else *(u32x4*)(xo + bj * 32) = pack8(v0, v1);
;                     ss += (v0[0] * v0[0] + v0[1] * v0[1]) + (v0[2] * v0[2] + v0[3] * v0[3]) + (v1[0] * v1[0] + v1[1] * v1[1]) + (v1[2] * v1[2] + v1[3] * v1[3]);
;                 }
;                 ss = fq_sum(ss);
;                 if (fq == 0) ssx[(size_t)row * 32 + u.pn * 4 + wc] = ss;
.LBB0_655:
	s_or_b64 exec, exec, s[16:17]
	ds_read_b32 v6, v146 offset:2560
	v_add_u32_e32 v2, 0x80, v142
	v_ashrrev_i32_e32 v3, 31, v2
	s_waitcnt lgkmcnt(0)
	v_lshlrev_b64 v[4:5], 12, v[2:3]
	v_lshl_add_u64 v[4:5], s[54:55], 0, v[4:5]
	v_pk_mul_f32 v[8:9], v[104:105], v[6:7] op_sel_hi:[1,0]
	v_pk_mul_f32 v[12:13], v[102:103], v[6:7] op_sel_hi:[1,0]
	v_lshl_add_u64 v[10:11], v[140:141], 1, v[4:5]
	v_pk_mul_f32 v[14:15], v[112:113], v[6:7] op_sel_hi:[1,0]
	v_pk_mul_f32 v[16:17], v[110:111], v[6:7] op_sel_hi:[1,0]
	v_cvt_pk_bf16_f32 v5, v8, v9
	v_mul_f32_e32 v7, v13, v13
	v_mul_f32_e32 v9, v9, v9
	v_fmac_f32_e32 v7, v12, v12
	v_fmac_f32_e32 v9, v8, v8
	v_mul_f32_e32 v8, v17, v17
	v_add_f32_e32 v7, v7, v9
	v_fmac_f32_e32 v8, v16, v16
	v_add_f32_e32 v7, v8, v7
	v_mul_f32_e32 v8, v15, v15
	v_fmac_f32_e32 v8, v14, v14
	v_add_f32_e32 v7, v8, v7
	v_cvt_pk_bf16_f32 v4, v12, v13
	v_pk_mul_f32 v[8:9], v[100:101], v[6:7] op_sel_hi:[1,0]
	v_pk_mul_f32 v[12:13], v[98:99], v[6:7] op_sel_hi:[1,0]
	v_pk_mul_f32 v[18:19], v[108:109], v[6:7] op_sel_hi:[1,0]
	v_pk_mul_f32 v[20:21], v[106:107], v[6:7] op_sel_hi:[1,0]
	v_mul_f32_e32 v6, v13, v13
	v_mul_f32_e32 v22, v9, v9
	v_fmac_f32_e32 v6, v12, v12
	v_fmac_f32_e32 v22, v8, v8
	v_add_f32_e32 v6, v6, v22
	v_mul_f32_e32 v22, v21, v21
	v_fmac_f32_e32 v22, v20, v20
	v_add_f32_e32 v6, v22, v6
	v_mul_f32_e32 v22, v19, v19
	v_fmac_f32_e32 v22, v18, v18
	v_add_f32_e32 v6, v22, v6
	v_add_f32_e32 v22, v7, v6
	ds_bpermute_b32 v23, v145, v22
	v_cvt_pk_bf16_f32 v6, v16, v17
	v_cvt_pk_bf16_f32 v7, v14, v15
	ds_write_b128 v161, v[4:7]
	s_waitcnt lgkmcnt(0)
	s_nop 0
	v_add_f32_e32 v4, v22, v23
	ds_bpermute_b32 v5, v144, v4
	v_cvt_pk_bf16_f32 v6, v12, v13
	v_cvt_pk_bf16_f32 v7, v8, v9
	v_cvt_pk_bf16_f32 v8, v20, v21
	v_cvt_pk_bf16_f32 v9, v18, v19
	ds_write_b128 v161, v[6:9] offset:64
	ds_read_b128 v[168:171], v160
	ds_read_b128 v[172:175], v160 offset:1152
	v_lshl_add_u64 v[166:167], v[10:11], 0, v[162:163]
	s_waitcnt lgkmcnt(0)
	global_store_dwordx4 v[166:167], v[168:171], off
	v_lshl_add_u64 v[166:167], v[10:11], 0, v[164:165]
	s_nop 0
	global_store_dwordx4 v[166:167], v[172:175], off
	s_and_saveexec_b64 s[16:17], s[40:41]
	s_cbranch_execz .LBB0_657
	v_lshlrev_b64 v[2:3], 7, v[2:3]
	v_lshl_add_u64 v[2:3], s[56:57], 0, v[2:3]
	v_lshl_add_u64 v[2:3], s[14:15], 2, v[2:3]
	s_lshl_b32 s44, s95, 2
	s_waitcnt lgkmcnt(0)
	v_add_f32_e32 v4, v4, v5
	v_lshl_add_u64 v[2:3], v[2:3], 0, s[44:45]
	global_store_dword v[2:3], v4, off
.LBB0_657:
	s_or_b64 exec, exec, s[16:17]
	ds_read_b32 v6, v146 offset:2624
	v_add_u32_e32 v2, 0x90, v142
	v_ashrrev_i32_e32 v3, 31, v2
	s_waitcnt lgkmcnt(0)
	v_lshlrev_b64 v[4:5], 12, v[2:3]
	v_lshl_add_u64 v[4:5], s[54:55], 0, v[4:5]
	v_pk_mul_f32 v[8:9], v[88:89], v[6:7] op_sel_hi:[1,0]
	v_pk_mul_f32 v[12:13], v[86:87], v[6:7] op_sel_hi:[1,0]
	v_lshl_add_u64 v[10:11], v[140:141], 1, v[4:5]
	v_pk_mul_f32 v[14:15], v[96:97], v[6:7] op_sel_hi:[1,0]
	v_pk_mul_f32 v[16:17], v[94:95], v[6:7] op_sel_hi:[1,0]
	v_cvt_pk_bf16_f32 v5, v8, v9
	v_mul_f32_e32 v7, v13, v13
	v_mul_f32_e32 v9, v9, v9
	v_fmac_f32_e32 v7, v12, v12
	v_fmac_f32_e32 v9, v8, v8
	v_mul_f32_e32 v8, v17, v17
	v_add_f32_e32 v7, v7, v9
	v_fmac_f32_e32 v8, v16, v16
	v_add_f32_e32 v7, v8, v7
	v_mul_f32_e32 v8, v15, v15
	v_fmac_f32_e32 v8, v14, v14
	v_add_f32_e32 v7, v8, v7
	v_cvt_pk_bf16_f32 v4, v12, v13
	v_pk_mul_f32 v[8:9], v[84:85], v[6:7] op_sel_hi:[1,0]
	v_pk_mul_f32 v[12:13], v[82:83], v[6:7] op_sel_hi:[1,0]
	v_pk_mul_f32 v[18:19], v[92:93], v[6:7] op_sel_hi:[1,0]
	v_pk_mul_f32 v[20:21], v[90:91], v[6:7] op_sel_hi:[1,0]
	v_mul_f32_e32 v6, v13, v13
	v_mul_f32_e32 v22, v9, v9
	v_fmac_f32_e32 v6, v12, v12
	v_fmac_f32_e32 v22, v8, v8
	v_add_f32_e32 v6, v6, v22
	v_mul_f32_e32 v22, v21, v21
	v_fmac_f32_e32 v22, v20, v20
	v_add_f32_e32 v6, v22, v6
	v_mul_f32_e32 v22, v19, v19
	v_fmac_f32_e32 v22, v18, v18
	v_add_f32_e32 v6, v22, v6
	v_add_f32_e32 v22, v7, v6
	ds_bpermute_b32 v23, v145, v22
	v_cvt_pk_bf16_f32 v6, v16, v17
	v_cvt_pk_bf16_f32 v7, v14, v15
	ds_write_b128 v161, v[4:7]
	s_waitcnt lgkmcnt(0)
	s_nop 0
	v_add_f32_e32 v4, v22, v23
	ds_bpermute_b32 v5, v144, v4
	v_cvt_pk_bf16_f32 v6, v12, v13
	v_cvt_pk_bf16_f32 v7, v8, v9
	v_cvt_pk_bf16_f32 v8, v20, v21
	v_cvt_pk_bf16_f32 v9, v18, v19
	ds_write_b128 v161, v[6:9] offset:64
	ds_read_b128 v[176:179], v160
	ds_read_b128 v[180:183], v160 offset:1152
	v_lshl_add_u64 v[166:167], v[10:11], 0, v[162:163]
	s_waitcnt lgkmcnt(0)
	global_store_dwordx4 v[166:167], v[176:179], off
	v_lshl_add_u64 v[166:167], v[10:11], 0, v[164:165]
	s_nop 0
	global_store_dwordx4 v[166:167], v[180:183], off
	s_and_saveexec_b64 s[16:17], s[40:41]
	s_cbranch_execz .LBB0_659
	v_lshlrev_b64 v[2:3], 7, v[2:3]
	v_lshl_add_u64 v[2:3], s[56:57], 0, v[2:3]
	v_lshl_add_u64 v[2:3], s[14:15], 2, v[2:3]
	s_lshl_b32 s44, s95, 2
	s_waitcnt lgkmcnt(0)
	v_add_f32_e32 v4, v4, v5
	v_lshl_add_u64 v[2:3], v[2:3], 0, s[44:45]
	global_store_dword v[2:3], v4, off
; __device__ __forceinline__ float fq_sum(float v) { v += __shfl_xor(v, 16); v += __shfl_xor(v, 32); return v; }
; __device__ __forceinline__ u32x4 pack8(f32x4 a, f32x4 b) { u32x4 w; w.x = pk2(a[0], a[1]); w.y = pk2(a[2], a[3]); w.z = pk2(b[0], b[1]); w.w = pk2(b[2], b[3]); return w; }
;     __device__ __forceinline__ void operator()(const f32x4 (&acc)[2][2][4][2], const pg8::Unit& u, int ui, int wr, int wc, int fr, int fq) const {
;     ...
;                 const int row = row0 + ai * 128 + m * 16;
;                 const float rb = rl[ai * 128 + m * 16];
;                 float* o = out + (size_t)row * DM + col0; bf16_t* xo = xb + (size_t)row * DM + col0;
;                 float ss = 0.f;
; #pragma unroll
;                 for (int bj = 0; bj < 2; ++bj) {
;                     const f32x4 v0 = acc[ai][bj][m][0] * rb, v1 = acc[ai][bj][m][1] * rb;
;                     if (last) { *(f32x4*)(o + bj * 32) = v0; *(f32x4*)(o + bj * 32 + 4) = v1; }
;                     else *(u32x4*)(xo + bj * 32) = pack8(v0, v1);
;                     ss += (v0[0] * v0[0] + v0[1] * v0[1]) + (v0[2] * v0[2] + v0[3] * v0[3]) + (v1[0] * v1[0] + v1[1] * v1[1]) + (v1[2] * v1[2] + v1[3] * v1[3]);
;                 }
;                 ss = fq_sum(ss);
;                 if (fq == 0) ssx[(size_t)row * 32 + u.pn * 4 + wc] = ss;
.LBB0_659:
	s_or_b64 exec, exec, s[16:17]
	ds_read_b32 v6, v146 offset:2688
	v_add_u32_e32 v2, 0xa0, v142
	v_ashrrev_i32_e32 v3, 31, v2
	s_waitcnt lgkmcnt(0)
	v_lshlrev_b64 v[4:5], 12, v[2:3]
	v_lshl_add_u64 v[4:5], s[54:55], 0, v[4:5]
	v_pk_mul_f32 v[8:9], v[72:73], v[6:7] op_sel_hi:[1,0]
	v_pk_mul_f32 v[12:13], v[70:71], v[6:7] op_sel_hi:[1,0]
	v_lshl_add_u64 v[10:11], v[140:141], 1, v[4:5]
	v_pk_mul_f32 v[14:15], v[80:81], v[6:7] op_sel_hi:[1,0]
	v_pk_mul_f32 v[16:17], v[78:79], v[6:7] op_sel_hi:[1,0]
	v_cvt_pk_bf16_f32 v5, v8, v9
	v_mul_f32_e32 v7, v13, v13
	v_mul_f32_e32 v9, v9, v9
	v_fmac_f32_e32 v7, v12, v12
	v_fmac_f32_e32 v9, v8, v8
	v_mul_f32_e32 v8, v17, v17
	v_add_f32_e32 v7, v7, v9
	v_fmac_f32_e32 v8, v16, v16
	v_add_f32_e32 v7, v8, v7
	v_mul_f32_e32 v8, v15, v15
	v_fmac_f32_e32 v8, v14, v14
	v_add_f32_e32 v7, v8, v7
	v_cvt_pk_bf16_f32 v4, v12, v13
	v_pk_mul_f32 v[8:9], v[68:69], v[6:7] op_sel_hi:[1,0]
	v_pk_mul_f32 v[12:13], v[66:67], v[6:7] op_sel_hi:[1,0]
	v_pk_mul_f32 v[18:19], v[76:77], v[6:7] op_sel_hi:[1,0]
	v_pk_mul_f32 v[20:21], v[74:75], v[6:7] op_sel_hi:[1,0]
	v_mul_f32_e32 v6, v13, v13
	v_mul_f32_e32 v22, v9, v9
	v_fmac_f32_e32 v6, v12, v12
	v_fmac_f32_e32 v22, v8, v8
	v_add_f32_e32 v6, v6, v22
	v_mul_f32_e32 v22, v21, v21
	v_fmac_f32_e32 v22, v20, v20
	v_add_f32_e32 v6, v22, v6
	v_mul_f32_e32 v22, v19, v19
	v_fmac_f32_e32 v22, v18, v18
	v_add_f32_e32 v6, v22, v6
	v_add_f32_e32 v22, v7, v6
	ds_bpermute_b32 v23, v145, v22
	v_cvt_pk_bf16_f32 v6, v16, v17
	v_cvt_pk_bf16_f32 v7, v14, v15
	ds_write_b128 v161, v[4:7]
	s_waitcnt lgkmcnt(0)
	s_nop 0
	v_add_f32_e32 v4, v22, v23
	ds_bpermute_b32 v5, v144, v4
	v_cvt_pk_bf16_f32 v6, v12, v13
	v_cvt_pk_bf16_f32 v7, v8, v9
	v_cvt_pk_bf16_f32 v8, v20, v21
	v_cvt_pk_bf16_f32 v9, v18, v19
	ds_write_b128 v161, v[6:9] offset:64
	ds_read_b128 v[168:171], v160
	ds_read_b128 v[172:175], v160 offset:1152
	v_lshl_add_u64 v[166:167], v[10:11], 0, v[162:163]
	s_waitcnt lgkmcnt(0)
	global_store_dwordx4 v[166:167], v[168:171], off
	v_lshl_add_u64 v[166:167], v[10:11], 0, v[164:165]
	s_nop 0
	global_store_dwordx4 v[166:167], v[172:175], off
	s_and_saveexec_b64 s[16:17], s[40:41]
	s_cbranch_execz .LBB0_661
	v_lshlrev_b64 v[2:3], 7, v[2:3]
	v_lshl_add_u64 v[2:3], s[56:57], 0, v[2:3]
	v_lshl_add_u64 v[2:3], s[14:15], 2, v[2:3]
	s_lshl_b32 s44, s95, 2
	s_waitcnt lgkmcnt(0)
	v_add_f32_e32 v4, v4, v5
	v_lshl_add_u64 v[2:3], v[2:3], 0, s[44:45]
	global_store_dword v[2:3], v4, off
.LBB0_661:
	s_or_b64 exec, exec, s[16:17]
	ds_read_b32 v6, v146 offset:2752
	v_add_u32_e32 v2, 0xb0, v142
	v_ashrrev_i32_e32 v3, 31, v2
	s_waitcnt lgkmcnt(0)
	v_lshlrev_b64 v[4:5], 12, v[2:3]
	v_lshl_add_u64 v[4:5], s[54:55], 0, v[4:5]
	v_pk_mul_f32 v[8:9], v[52:53], v[6:7] op_sel_hi:[1,0]
	v_pk_mul_f32 v[12:13], v[50:51], v[6:7] op_sel_hi:[1,0]
	v_lshl_add_u64 v[10:11], v[140:141], 1, v[4:5]
	v_pk_mul_f32 v[14:15], v[64:65], v[6:7] op_sel_hi:[1,0]
	v_pk_mul_f32 v[16:17], v[62:63], v[6:7] op_sel_hi:[1,0]
	v_cvt_pk_bf16_f32 v5, v8, v9
	v_mul_f32_e32 v7, v13, v13
	v_mul_f32_e32 v9, v9, v9
	v_fmac_f32_e32 v7, v12, v12
	v_fmac_f32_e32 v9, v8, v8
	v_mul_f32_e32 v8, v17, v17
	v_add_f32_e32 v7, v7, v9
	v_fmac_f32_e32 v8, v16, v16
	v_add_f32_e32 v7, v8, v7
	v_mul_f32_e32 v8, v15, v15
	v_fmac_f32_e32 v8, v14, v14
	v_add_f32_e32 v7, v8, v7
	v_cvt_pk_bf16_f32 v4, v12, v13
	v_pk_mul_f32 v[8:9], v[48:49], v[6:7] op_sel_hi:[1,0]
	v_pk_mul_f32 v[12:13], v[46:47], v[6:7] op_sel_hi:[1,0]
	v_pk_mul_f32 v[18:19], v[60:61], v[6:7] op_sel_hi:[1,0]
	v_pk_mul_f32 v[20:21], v[58:59], v[6:7] op_sel_hi:[1,0]
	v_mul_f32_e32 v6, v13, v13
	v_mul_f32_e32 v22, v9, v9
	v_fmac_f32_e32 v6, v12, v12
	v_fmac_f32_e32 v22, v8, v8
	v_add_f32_e32 v6, v6, v22
	v_mul_f32_e32 v22, v21, v21
	v_fmac_f32_e32 v22, v20, v20
	v_add_f32_e32 v6, v22, v6
	v_mul_f32_e32 v22, v19, v19
	v_fmac_f32_e32 v22, v18, v18
	v_add_f32_e32 v6, v22, v6
	v_add_f32_e32 v22, v7, v6
	ds_bpermute_b32 v23, v145, v22
	v_cvt_pk_bf16_f32 v6, v16, v17
	v_cvt_pk_bf16_f32 v7, v14, v15
	ds_write_b128 v161, v[4:7]
	s_waitcnt lgkmcnt(0)
	s_nop 0
	v_add_f32_e32 v4, v22, v23
	ds_bpermute_b32 v5, v144, v4
	v_cvt_pk_bf16_f32 v6, v12, v13
	v_cvt_pk_bf16_f32 v7, v8, v9
	v_cvt_pk_bf16_f32 v8, v20, v21
	v_cvt_pk_bf16_f32 v9, v18, v19
	ds_write_b128 v161, v[6:9] offset:64
	ds_read_b128 v[176:179], v160
	ds_read_b128 v[180:183], v160 offset:1152
	v_lshl_add_u64 v[166:167], v[10:11], 0, v[162:163]
	s_waitcnt lgkmcnt(0)
	global_store_dwordx4 v[166:167], v[176:179], off
	v_lshl_add_u64 v[166:167], v[10:11], 0, v[164:165]
	s_nop 0
	global_store_dwordx4 v[166:167], v[180:183], off
	s_and_saveexec_b64 s[16:17], s[40:41]
	s_cbranch_execz .LBB0_663
	v_lshlrev_b64 v[2:3], 7, v[2:3]
	v_lshl_add_u64 v[2:3], s[56:57], 0, v[2:3]
	v_lshl_add_u64 v[2:3], s[14:15], 2, v[2:3]
	s_lshl_b32 s44, s95, 2
	s_waitcnt lgkmcnt(0)
	v_add_f32_e32 v4, v4, v5
	v_lshl_add_u64 v[2:3], v[2:3], 0, s[44:45]
	global_store_dword v[2:3], v4, off
